# PH7 sample down-proj tail moved from workgroups 60..91 to 48..79 so it no longer lands on workgroups that also host a sample up-GEMM unit
# speedup vs baseline: 1.0280x; 1.0044x over previous
; __device__ __forceinline__ KArgs kargs() { KArgs p = (KArgs)__builtin_amdgcn_kernarg_segment_ptr(); asm volatile("" : "+s"(p)); return p; }
; __global__ void __launch_bounds__(512, 2) fwd_kernel(Args a) {
;     ...
;     if (bx >= 60 && bx < 92) {
;         KArgs k = kargs();
;         float* out = k->out; const bf16* ACT = WSP(bf16, WS_ACT); const bf16* WDN = WSP(bf16, WS_WDN); unsigned* CTR = WSP(unsigned, WS_CTR);
;         if (tid < 64) { unsigned sp = 0;
;             while ((unsigned)__builtin_amdgcn_readfirstlane(__hip_atomic_load(CTR + 128, __ATOMIC_RELAXED, __HIP_MEMORY_SCOPE_AGENT)) < 22u) { __builtin_amdgcn_s_sleep(8); if (++sp > (1u << 20)) break; }
;             __builtin_amdgcn_fence(__ATOMIC_ACQUIRE, "agent"); asm volatile("s_waitcnt vmcnt(0)" ::: "memory"); }
.LBB0_1118:
	s_sub_i32 s0, s2, 48
	s_cmp_gt_u32 s0, 31
	s_cbranch_scc1 .LBB0_1126
	s_mov_b64 s[0:1], s[76:77]
	s_load_dwordx4 s[8:11], s[0:1], 0xd0
	v_cmp_gt_u32_e32 vcc, 64, v152
	s_and_saveexec_b64 s[12:13], vcc
	v_readlane_b32 s18, v236, 3
	s_cbranch_execz .LBB0_1125
	s_waitcnt lgkmcnt(0)
	s_add_u32 s14, s10, 0x1a28200
	s_addc_u32 s15, s11, 0
	s_mov_b32 s0, 0x100001
	v_mov_b32_e32 v0, 0
	s_branch .LBB0_1122

; __global__ void __launch_bounds__(512, 2) fwd_kernel(Args a) {
;     ...
;         const int r16 = lane & 15, q4 = lane >> 4, cb0 = (bx - 60) * 2;
;         f32x4 pa[2][8];
; #pragma unroll
;         for (int j = 0; j < 2; ++j)
; #pragma unroll
;             for (int rbk = 0; rbk < 8; ++rbk) pa[j][rbk] = (f32x4){0.f, 0.f, 0.f, 0.f};
;         const bf16* wp = WDN + ((size_t)(16 * cb0 + r16) * FF + 352 * wave + 8 * q4);
;         const bf16* ap = ACT + ((size_t)(MP + r16) * FF + 352 * wave + 8 * q4);
; #pragma unroll
;         for (int ks = 0; ks < 11; ++ks) {
;             const bf16x8 wf0 = *(const bf16x8*)(wp + 32 * ks), wf1 = *(const bf16x8*)(wp + (size_t)16 * FF + 32 * ks);
; #pragma unroll
;             for (int rbk = 0; rbk < 8; ++rbk) { const bf16x8 af = *(const bf16x8*)(ap + (size_t)rbk * 16 * FF + 32 * ks);
;                 pa[0][rbk] = __builtin_amdgcn_mfma_f32_16x16x32_bf16(wf0, af, pa[0][rbk], 0, 0, 0); pa[1][rbk] = __builtin_amdgcn_mfma_f32_16x16x32_bf16(wf1, af, pa[1][rbk], 0, 0, 0); }
;             asm volatile("" ::: "memory");
;         }
.LBB0_1125:
	s_or_b64 exec, exec, s[12:13]
	s_lshl_b32 s0, s2, 1
	s_addk_i32 s0, 0xffa0
	v_lshl_or_b32 v2, s0, 4, v157
	s_movk_i32 s1, 0x1600
	s_waitcnt lgkmcnt(0)
	v_mov_b64_e32 v[0:1], s[10:11]
	s_mul_i32 s4, s18, 0x160
	s_mov_b32 s5, 0
	v_mad_u64_u32 v[0:1], s[6:7], v2, s1, v[0:1]
	v_lshl_add_u64 v[0:1], s[4:5], 1, v[0:1]
	v_mov_b32_e32 v159, 0
	v_lshl_add_u64 v[88:89], v[0:1], 0, v[158:159]
	s_movk_i32 s1, 0xb00
	v_mov_b32_e32 v0, s4
	v_mad_u32_u24 v0, v157, s1, v0
	v_add_u32_e32 v0, 0x2c00000, v0
	v_mov_b32_e32 v1, v159
	v_lshl_add_u64 v[0:1], v[0:1], 1, s[10:11]
	s_mov_b32 s1, 0xf80000
	v_lshl_add_u64 v[92:93], v[0:1], 0, v[158:159]
	v_add_co_u32_e32 v0, vcc, s1, v88
	s_mov_b32 s1, 0xf96000
	s_nop 0
	v_addc_co_u32_e32 v1, vcc, 0, v89, vcc
	s_waitcnt vmcnt(0)
	s_barrier
	global_load_dwordx4 v[20:23], v[0:1], off
	v_add_co_u32_e32 v0, vcc, s1, v88
	s_mov_b32 s1, 0x1b00000
	s_nop 0
	v_addc_co_u32_e32 v1, vcc, 0, v89, vcc
	v_add_co_u32_e32 v2, vcc, s1, v92
	s_mov_b32 s1, 0x1b16000
	s_nop 0
	v_addc_co_u32_e32 v3, vcc, 0, v93, vcc
	global_load_dwordx4 v[6:9], v[2:3], off
	global_load_dwordx4 v[24:27], v[0:1], off
	v_add_co_u32_e32 v2, vcc, s1, v92
	s_mov_b32 s1, 0x1b2c000
	s_nop 0
	v_addc_co_u32_e32 v3, vcc, 0, v93, vcc
	v_add_co_u32_e32 v4, vcc, s1, v92
	global_load_dwordx4 v[10:13], v[2:3], off
	s_nop 0
	v_addc_co_u32_e32 v5, vcc, 0, v93, vcc
	global_load_dwordx4 v[14:17], v[4:5], off
	s_mov_b32 s1, 0x1b42000
	s_mov_b64 s[4:5], 0xf80000
	s_waitcnt vmcnt(3)
	v_mfma_f32_16x16x32_bf16 v[28:31], v[20:23], v[6:9], 0
	s_waitcnt vmcnt(2)
	v_mfma_f32_16x16x32_bf16 v[32:35], v[24:27], v[6:9], 0
	v_add_co_u32_e32 v6, vcc, s1, v92
	s_mov_b32 s1, 0x1b58000
	s_nop 0
	v_addc_co_u32_e32 v7, vcc, 0, v93, vcc
	v_add_co_u32_e32 v8, vcc, s1, v92
	s_waitcnt vmcnt(1)
	v_mfma_f32_16x16x32_bf16 v[36:39], v[20:23], v[10:13], 0
	v_addc_co_u32_e32 v9, vcc, 0, v93, vcc
	global_load_dwordx4 v[44:47], v[6:7], off
	v_mfma_f32_16x16x32_bf16 v[40:43], v[24:27], v[10:13], 0
	s_mov_b32 s1, 0x1b6e000
	v_add_co_u32_e32 v10, vcc, s1, v92
	s_waitcnt vmcnt(1)
	v_mfma_f32_16x16x32_bf16 v[48:51], v[20:23], v[14:17], 0
	v_addc_co_u32_e32 v11, vcc, 0, v93, vcc
	s_mov_b32 s1, 0x1b84000
	v_mfma_f32_16x16x32_bf16 v[52:55], v[24:27], v[14:17], 0
	global_load_dwordx4 v[12:15], v[8:9], off
	global_load_dwordx4 v[16:19], v[10:11], off
	s_waitcnt vmcnt(2)
	v_mfma_f32_16x16x32_bf16 v[56:59], v[20:23], v[44:47], 0
	s_waitcnt vmcnt(1)
	v_mfma_f32_16x16x32_bf16 v[60:63], v[20:23], v[12:15], 0
	v_mfma_f32_16x16x32_bf16 v[64:67], v[24:27], v[12:15], 0
	v_add_co_u32_e32 v12, vcc, s1, v92
	s_mov_b32 s1, 0x1b9a000
	s_nop 0
	v_addc_co_u32_e32 v13, vcc, 0, v93, vcc
	v_add_co_u32_e32 v14, vcc, s1, v92
	global_load_dwordx4 v[72:75], v[12:13], off
	s_nop 0
	v_addc_co_u32_e32 v15, vcc, 0, v93, vcc
	global_load_dwordx4 v[80:83], v[14:15], off
	s_waitcnt vmcnt(2)
	v_mfma_f32_16x16x32_bf16 v[68:71], v[20:23], v[16:19], 0
	v_readlane_b32 s1, v236, 0
	global_load_dwordx4 v[96:99], v[2:3], off offset:64
	v_mfma_f32_16x16x32_bf16 v[76:79], v[24:27], v[16:19], 0
	v_lshl_add_u64 v[16:17], v[88:89], 0, s[4:5]
	global_load_dwordx4 v[88:91], v[16:17], off offset:64
	s_mov_b64 s[4:5], 0x1b00000
	v_mfma_f32_16x16x32_bf16 v[44:47], v[24:27], v[44:47], 0
	v_lshl_add_u64 v[18:19], v[92:93], 0, s[4:5]
	global_load_dwordx4 v[92:95], v[18:19], off offset:64
	s_lshl_b32 s4, s18, 5
	s_waitcnt vmcnt(4)
	v_mfma_f32_16x16x32_bf16 v[84:87], v[20:23], v[72:75], 0
	s_and_b32 s4, s4, 0x60
	v_mfma_f32_16x16x32_bf16 v[72:75], v[24:27], v[72:75], 0
	s_waitcnt vmcnt(3)
	v_mfma_f32_16x16x32_bf16 v[20:23], v[20:23], v[80:83], 0
	v_mfma_f32_16x16x32_bf16 v[24:27], v[24:27], v[80:83], 0
	global_load_dwordx4 v[80:83], v[0:1], off offset:64
	s_waitcnt vmcnt(1)
	v_mfma_f32_16x16x32_bf16 v[28:31], v[88:91], v[92:95], v[28:31]
	v_mfma_f32_16x16x32_bf16 v[36:39], v[88:91], v[96:99], v[36:39]
	s_waitcnt vmcnt(0)
	v_mfma_f32_16x16x32_bf16 v[32:35], v[80:83], v[92:95], v[32:35]
	global_load_dwordx4 v[92:95], v[4:5], off offset:64
	v_mfma_f32_16x16x32_bf16 v[40:43], v[80:83], v[96:99], v[40:43]
	global_load_dwordx4 v[96:99], v[6:7], off offset:64
	s_waitcnt vmcnt(1)
	v_mfma_f32_16x16x32_bf16 v[48:51], v[88:91], v[92:95], v[48:51]
	v_mfma_f32_16x16x32_bf16 v[52:55], v[80:83], v[92:95], v[52:55]
	global_load_dwordx4 v[92:95], v[8:9], off offset:64
	s_waitcnt vmcnt(1)
	v_mfma_f32_16x16x32_bf16 v[56:59], v[88:91], v[96:99], v[56:59]
	v_mfma_f32_16x16x32_bf16 v[44:47], v[80:83], v[96:99], v[44:47]
	global_load_dwordx4 v[96:99], v[10:11], off offset:64
	s_waitcnt vmcnt(1)
	v_mfma_f32_16x16x32_bf16 v[60:63], v[88:91], v[92:95], v[60:63]
	v_mfma_f32_16x16x32_bf16 v[64:67], v[80:83], v[92:95], v[64:67]
	global_load_dwordx4 v[92:95], v[12:13], off offset:64
	s_waitcnt vmcnt(1)
	v_mfma_f32_16x16x32_bf16 v[68:71], v[88:91], v[96:99], v[68:71]
	v_mfma_f32_16x16x32_bf16 v[76:79], v[80:83], v[96:99], v[76:79]
	global_load_dwordx4 v[96:99], v[14:15], off offset:64
	s_waitcnt vmcnt(1)
	v_mfma_f32_16x16x32_bf16 v[84:87], v[88:91], v[92:95], v[84:87]
	v_mfma_f32_16x16x32_bf16 v[72:75], v[80:83], v[92:95], v[72:75]
	global_load_dwordx4 v[92:95], v[16:17], off offset:128
	s_waitcnt vmcnt(1)
	v_mfma_f32_16x16x32_bf16 v[24:27], v[80:83], v[96:99], v[24:27]
	global_load_dwordx4 v[80:83], v[0:1], off offset:128
	v_mfma_f32_16x16x32_bf16 v[20:23], v[88:91], v[96:99], v[20:23]
	global_load_dwordx4 v[88:91], v[18:19], off offset:128
	global_load_dwordx4 v[96:99], v[2:3], off offset:128
	s_waitcnt vmcnt(1)
	v_mfma_f32_16x16x32_bf16 v[28:31], v[92:95], v[88:91], v[28:31]
	v_mfma_f32_16x16x32_bf16 v[32:35], v[80:83], v[88:91], v[32:35]
	global_load_dwordx4 v[88:91], v[4:5], off offset:128
	s_waitcnt vmcnt(1)
; __global__ void __launch_bounds__(512, 2) fwd_kernel(Args a) {
;     ...
;         for (int ks = 0; ks < 11; ++ks) {
;             const bf16x8 wf0 = *(const bf16x8*)(wp + 32 * ks), wf1 = *(const bf16x8*)(wp + (size_t)16 * FF + 32 * ks);
; #pragma unroll
;             for (int rbk = 0; rbk < 8; ++rbk) { const bf16x8 af = *(const bf16x8*)(ap + (size_t)rbk * 16 * FF + 32 * ks);
;                 pa[0][rbk] = __builtin_amdgcn_mfma_f32_16x16x32_bf16(wf0, af, pa[0][rbk], 0, 0, 0); pa[1][rbk] = __builtin_amdgcn_mfma_f32_16x16x32_bf16(wf1, af, pa[1][rbk], 0, 0, 0); }
;             asm volatile("" ::: "memory");
;         }
	v_mfma_f32_16x16x32_bf16 v[36:39], v[92:95], v[96:99], v[36:39]
	v_mfma_f32_16x16x32_bf16 v[40:43], v[80:83], v[96:99], v[40:43]
	global_load_dwordx4 v[96:99], v[6:7], off offset:128
	s_waitcnt vmcnt(1)
	v_mfma_f32_16x16x32_bf16 v[48:51], v[92:95], v[88:91], v[48:51]
	v_mfma_f32_16x16x32_bf16 v[52:55], v[80:83], v[88:91], v[52:55]
	global_load_dwordx4 v[88:91], v[8:9], off offset:128
	s_waitcnt vmcnt(1)
	v_mfma_f32_16x16x32_bf16 v[56:59], v[92:95], v[96:99], v[56:59]
	v_mfma_f32_16x16x32_bf16 v[44:47], v[80:83], v[96:99], v[44:47]
	global_load_dwordx4 v[96:99], v[10:11], off offset:128
	s_waitcnt vmcnt(1)
	v_mfma_f32_16x16x32_bf16 v[60:63], v[92:95], v[88:91], v[60:63]
	v_mfma_f32_16x16x32_bf16 v[64:67], v[80:83], v[88:91], v[64:67]
	global_load_dwordx4 v[88:91], v[12:13], off offset:128
	s_waitcnt vmcnt(1)
	v_mfma_f32_16x16x32_bf16 v[68:71], v[92:95], v[96:99], v[68:71]
	v_mfma_f32_16x16x32_bf16 v[76:79], v[80:83], v[96:99], v[76:79]
	global_load_dwordx4 v[96:99], v[14:15], off offset:128
	s_waitcnt vmcnt(1)
	v_mfma_f32_16x16x32_bf16 v[84:87], v[92:95], v[88:91], v[84:87]
	v_mfma_f32_16x16x32_bf16 v[72:75], v[80:83], v[88:91], v[72:75]
	global_load_dwordx4 v[88:91], v[16:17], off offset:192
	s_waitcnt vmcnt(1)
	v_mfma_f32_16x16x32_bf16 v[24:27], v[80:83], v[96:99], v[24:27]
	global_load_dwordx4 v[80:83], v[0:1], off offset:192
	v_mfma_f32_16x16x32_bf16 v[20:23], v[92:95], v[96:99], v[20:23]
	global_load_dwordx4 v[92:95], v[18:19], off offset:192
	global_load_dwordx4 v[96:99], v[2:3], off offset:192
	s_waitcnt vmcnt(1)
	v_mfma_f32_16x16x32_bf16 v[28:31], v[88:91], v[92:95], v[28:31]
	v_mfma_f32_16x16x32_bf16 v[32:35], v[80:83], v[92:95], v[32:35]
	global_load_dwordx4 v[92:95], v[4:5], off offset:192
	s_waitcnt vmcnt(1)
	v_mfma_f32_16x16x32_bf16 v[36:39], v[88:91], v[96:99], v[36:39]
	v_mfma_f32_16x16x32_bf16 v[40:43], v[80:83], v[96:99], v[40:43]
	global_load_dwordx4 v[96:99], v[6:7], off offset:192
	s_waitcnt vmcnt(1)
	v_mfma_f32_16x16x32_bf16 v[48:51], v[88:91], v[92:95], v[48:51]
	v_mfma_f32_16x16x32_bf16 v[52:55], v[80:83], v[92:95], v[52:55]
	global_load_dwordx4 v[92:95], v[8:9], off offset:192
	s_waitcnt vmcnt(1)
	v_mfma_f32_16x16x32_bf16 v[56:59], v[88:91], v[96:99], v[56:59]
	v_mfma_f32_16x16x32_bf16 v[44:47], v[80:83], v[96:99], v[44:47]
	global_load_dwordx4 v[96:99], v[10:11], off offset:192
	s_waitcnt vmcnt(1)
	v_mfma_f32_16x16x32_bf16 v[60:63], v[88:91], v[92:95], v[60:63]
	v_mfma_f32_16x16x32_bf16 v[64:67], v[80:83], v[92:95], v[64:67]
	global_load_dwordx4 v[92:95], v[12:13], off offset:192
	s_waitcnt vmcnt(1)
	v_mfma_f32_16x16x32_bf16 v[68:71], v[88:91], v[96:99], v[68:71]
	v_mfma_f32_16x16x32_bf16 v[76:79], v[80:83], v[96:99], v[76:79]
	global_load_dwordx4 v[96:99], v[14:15], off offset:192
	s_waitcnt vmcnt(1)
	v_mfma_f32_16x16x32_bf16 v[84:87], v[88:91], v[92:95], v[84:87]
	v_mfma_f32_16x16x32_bf16 v[72:75], v[80:83], v[92:95], v[72:75]
	global_load_dwordx4 v[92:95], v[16:17], off offset:256
	s_waitcnt vmcnt(1)
	v_mfma_f32_16x16x32_bf16 v[24:27], v[80:83], v[96:99], v[24:27]
	global_load_dwordx4 v[80:83], v[0:1], off offset:256
	v_mfma_f32_16x16x32_bf16 v[20:23], v[88:91], v[96:99], v[20:23]
	global_load_dwordx4 v[88:91], v[18:19], off offset:256
	global_load_dwordx4 v[96:99], v[2:3], off offset:256
	s_waitcnt vmcnt(1)
	v_mfma_f32_16x16x32_bf16 v[28:31], v[92:95], v[88:91], v[28:31]
	v_mfma_f32_16x16x32_bf16 v[32:35], v[80:83], v[88:91], v[32:35]
	global_load_dwordx4 v[88:91], v[4:5], off offset:256
	s_waitcnt vmcnt(1)
	v_mfma_f32_16x16x32_bf16 v[36:39], v[92:95], v[96:99], v[36:39]
	v_mfma_f32_16x16x32_bf16 v[40:43], v[80:83], v[96:99], v[40:43]
	global_load_dwordx4 v[96:99], v[6:7], off offset:256
	s_waitcnt vmcnt(1)
	v_mfma_f32_16x16x32_bf16 v[48:51], v[92:95], v[88:91], v[48:51]
	v_mfma_f32_16x16x32_bf16 v[52:55], v[80:83], v[88:91], v[52:55]
	global_load_dwordx4 v[88:91], v[8:9], off offset:256
	s_waitcnt vmcnt(1)
	v_mfma_f32_16x16x32_bf16 v[56:59], v[92:95], v[96:99], v[56:59]
	v_mfma_f32_16x16x32_bf16 v[44:47], v[80:83], v[96:99], v[44:47]
	global_load_dwordx4 v[96:99], v[10:11], off offset:256
	s_waitcnt vmcnt(1)
	v_mfma_f32_16x16x32_bf16 v[60:63], v[92:95], v[88:91], v[60:63]
	v_mfma_f32_16x16x32_bf16 v[64:67], v[80:83], v[88:91], v[64:67]
	global_load_dwordx4 v[88:91], v[12:13], off offset:256
	s_waitcnt vmcnt(1)
	v_mfma_f32_16x16x32_bf16 v[68:71], v[92:95], v[96:99], v[68:71]
	v_mfma_f32_16x16x32_bf16 v[76:79], v[80:83], v[96:99], v[76:79]
	global_load_dwordx4 v[96:99], v[14:15], off offset:256
	s_waitcnt vmcnt(1)
	v_mfma_f32_16x16x32_bf16 v[84:87], v[92:95], v[88:91], v[84:87]
	v_mfma_f32_16x16x32_bf16 v[72:75], v[80:83], v[88:91], v[72:75]
	global_load_dwordx4 v[88:91], v[16:17], off offset:320
	s_waitcnt vmcnt(1)
	v_mfma_f32_16x16x32_bf16 v[24:27], v[80:83], v[96:99], v[24:27]
	global_load_dwordx4 v[80:83], v[0:1], off offset:320
	v_mfma_f32_16x16x32_bf16 v[20:23], v[92:95], v[96:99], v[20:23]
	global_load_dwordx4 v[92:95], v[18:19], off offset:320
	global_load_dwordx4 v[96:99], v[2:3], off offset:320
	s_waitcnt vmcnt(1)
	v_mfma_f32_16x16x32_bf16 v[28:31], v[88:91], v[92:95], v[28:31]
	v_mfma_f32_16x16x32_bf16 v[32:35], v[80:83], v[92:95], v[32:35]
	global_load_dwordx4 v[92:95], v[4:5], off offset:320
	s_waitcnt vmcnt(1)
	v_mfma_f32_16x16x32_bf16 v[36:39], v[88:91], v[96:99], v[36:39]
	v_mfma_f32_16x16x32_bf16 v[40:43], v[80:83], v[96:99], v[40:43]
	global_load_dwordx4 v[96:99], v[6:7], off offset:320
	s_waitcnt vmcnt(1)
	v_mfma_f32_16x16x32_bf16 v[48:51], v[88:91], v[92:95], v[48:51]
	v_mfma_f32_16x16x32_bf16 v[52:55], v[80:83], v[92:95], v[52:55]
	global_load_dwordx4 v[92:95], v[8:9], off offset:320
	s_waitcnt vmcnt(1)
; __global__ void __launch_bounds__(512, 2) fwd_kernel(Args a) {
;     ...
;         for (int ks = 0; ks < 11; ++ks) {
;             const bf16x8 wf0 = *(const bf16x8*)(wp + 32 * ks), wf1 = *(const bf16x8*)(wp + (size_t)16 * FF + 32 * ks);
; #pragma unroll
;             for (int rbk = 0; rbk < 8; ++rbk) { const bf16x8 af = *(const bf16x8*)(ap + (size_t)rbk * 16 * FF + 32 * ks);
;                 pa[0][rbk] = __builtin_amdgcn_mfma_f32_16x16x32_bf16(wf0, af, pa[0][rbk], 0, 0, 0); pa[1][rbk] = __builtin_amdgcn_mfma_f32_16x16x32_bf16(wf1, af, pa[1][rbk], 0, 0, 0); }
;             asm volatile("" ::: "memory");
;         }
	v_mfma_f32_16x16x32_bf16 v[56:59], v[88:91], v[96:99], v[56:59]
	v_mfma_f32_16x16x32_bf16 v[44:47], v[80:83], v[96:99], v[44:47]
	global_load_dwordx4 v[96:99], v[10:11], off offset:320
	s_waitcnt vmcnt(1)
	v_mfma_f32_16x16x32_bf16 v[60:63], v[88:91], v[92:95], v[60:63]
	v_mfma_f32_16x16x32_bf16 v[64:67], v[80:83], v[92:95], v[64:67]
	global_load_dwordx4 v[92:95], v[12:13], off offset:320
	s_waitcnt vmcnt(1)
	v_mfma_f32_16x16x32_bf16 v[68:71], v[88:91], v[96:99], v[68:71]
	v_mfma_f32_16x16x32_bf16 v[76:79], v[80:83], v[96:99], v[76:79]
	global_load_dwordx4 v[96:99], v[14:15], off offset:320
	s_waitcnt vmcnt(1)
	v_mfma_f32_16x16x32_bf16 v[84:87], v[88:91], v[92:95], v[84:87]
	v_mfma_f32_16x16x32_bf16 v[72:75], v[80:83], v[92:95], v[72:75]
	global_load_dwordx4 v[92:95], v[16:17], off offset:384
	s_waitcnt vmcnt(1)
	v_mfma_f32_16x16x32_bf16 v[24:27], v[80:83], v[96:99], v[24:27]
	global_load_dwordx4 v[80:83], v[0:1], off offset:384
	v_mfma_f32_16x16x32_bf16 v[20:23], v[88:91], v[96:99], v[20:23]
	global_load_dwordx4 v[88:91], v[18:19], off offset:384
	global_load_dwordx4 v[96:99], v[2:3], off offset:384
	s_waitcnt vmcnt(1)
	v_mfma_f32_16x16x32_bf16 v[28:31], v[92:95], v[88:91], v[28:31]
	v_mfma_f32_16x16x32_bf16 v[32:35], v[80:83], v[88:91], v[32:35]
	global_load_dwordx4 v[88:91], v[4:5], off offset:384
	s_waitcnt vmcnt(1)
	v_mfma_f32_16x16x32_bf16 v[36:39], v[92:95], v[96:99], v[36:39]
	v_mfma_f32_16x16x32_bf16 v[40:43], v[80:83], v[96:99], v[40:43]
	global_load_dwordx4 v[96:99], v[6:7], off offset:384
	s_waitcnt vmcnt(1)
	v_mfma_f32_16x16x32_bf16 v[48:51], v[92:95], v[88:91], v[48:51]
	v_mfma_f32_16x16x32_bf16 v[52:55], v[80:83], v[88:91], v[52:55]
	global_load_dwordx4 v[88:91], v[8:9], off offset:384
	s_waitcnt vmcnt(1)
	v_mfma_f32_16x16x32_bf16 v[56:59], v[92:95], v[96:99], v[56:59]
	v_mfma_f32_16x16x32_bf16 v[44:47], v[80:83], v[96:99], v[44:47]
	global_load_dwordx4 v[96:99], v[10:11], off offset:384
	s_waitcnt vmcnt(1)
	v_mfma_f32_16x16x32_bf16 v[60:63], v[92:95], v[88:91], v[60:63]
	v_mfma_f32_16x16x32_bf16 v[64:67], v[80:83], v[88:91], v[64:67]
	global_load_dwordx4 v[88:91], v[12:13], off offset:384
	s_waitcnt vmcnt(1)
	v_mfma_f32_16x16x32_bf16 v[68:71], v[92:95], v[96:99], v[68:71]
	v_mfma_f32_16x16x32_bf16 v[76:79], v[80:83], v[96:99], v[76:79]
	global_load_dwordx4 v[96:99], v[14:15], off offset:384
	s_waitcnt vmcnt(1)
	v_mfma_f32_16x16x32_bf16 v[84:87], v[92:95], v[88:91], v[84:87]
	v_mfma_f32_16x16x32_bf16 v[72:75], v[80:83], v[88:91], v[72:75]
	global_load_dwordx4 v[88:91], v[16:17], off offset:448
	s_waitcnt vmcnt(1)
	v_mfma_f32_16x16x32_bf16 v[24:27], v[80:83], v[96:99], v[24:27]
	global_load_dwordx4 v[80:83], v[0:1], off offset:448
	v_mfma_f32_16x16x32_bf16 v[20:23], v[92:95], v[96:99], v[20:23]
	global_load_dwordx4 v[92:95], v[18:19], off offset:448
	global_load_dwordx4 v[96:99], v[2:3], off offset:448
	s_waitcnt vmcnt(1)
	v_mfma_f32_16x16x32_bf16 v[28:31], v[88:91], v[92:95], v[28:31]
	v_mfma_f32_16x16x32_bf16 v[32:35], v[80:83], v[92:95], v[32:35]
	global_load_dwordx4 v[92:95], v[4:5], off offset:448
	s_waitcnt vmcnt(1)
	v_mfma_f32_16x16x32_bf16 v[36:39], v[88:91], v[96:99], v[36:39]
	v_mfma_f32_16x16x32_bf16 v[40:43], v[80:83], v[96:99], v[40:43]
	global_load_dwordx4 v[96:99], v[6:7], off offset:448
	s_waitcnt vmcnt(1)
	v_mfma_f32_16x16x32_bf16 v[48:51], v[88:91], v[92:95], v[48:51]
	v_mfma_f32_16x16x32_bf16 v[52:55], v[80:83], v[92:95], v[52:55]
	global_load_dwordx4 v[92:95], v[8:9], off offset:448
	s_waitcnt vmcnt(1)
	v_mfma_f32_16x16x32_bf16 v[56:59], v[88:91], v[96:99], v[56:59]
	v_mfma_f32_16x16x32_bf16 v[44:47], v[80:83], v[96:99], v[44:47]
	global_load_dwordx4 v[96:99], v[10:11], off offset:448
	s_waitcnt vmcnt(1)
	v_mfma_f32_16x16x32_bf16 v[60:63], v[88:91], v[92:95], v[60:63]
	v_mfma_f32_16x16x32_bf16 v[64:67], v[80:83], v[92:95], v[64:67]
	global_load_dwordx4 v[92:95], v[12:13], off offset:448
	s_waitcnt vmcnt(1)
	v_mfma_f32_16x16x32_bf16 v[68:71], v[88:91], v[96:99], v[68:71]
	v_mfma_f32_16x16x32_bf16 v[76:79], v[80:83], v[96:99], v[76:79]
	global_load_dwordx4 v[96:99], v[14:15], off offset:448
	s_waitcnt vmcnt(1)
	v_mfma_f32_16x16x32_bf16 v[84:87], v[88:91], v[92:95], v[84:87]
	v_mfma_f32_16x16x32_bf16 v[72:75], v[80:83], v[92:95], v[72:75]
	global_load_dwordx4 v[92:95], v[16:17], off offset:512
	s_waitcnt vmcnt(1)
	v_mfma_f32_16x16x32_bf16 v[24:27], v[80:83], v[96:99], v[24:27]
	global_load_dwordx4 v[80:83], v[0:1], off offset:512
	v_mfma_f32_16x16x32_bf16 v[20:23], v[88:91], v[96:99], v[20:23]
	global_load_dwordx4 v[88:91], v[18:19], off offset:512
	global_load_dwordx4 v[96:99], v[2:3], off offset:512
	s_waitcnt vmcnt(1)
	v_mfma_f32_16x16x32_bf16 v[28:31], v[92:95], v[88:91], v[28:31]
	v_mfma_f32_16x16x32_bf16 v[32:35], v[80:83], v[88:91], v[32:35]
	global_load_dwordx4 v[88:91], v[4:5], off offset:512
	s_waitcnt vmcnt(1)
	v_mfma_f32_16x16x32_bf16 v[36:39], v[92:95], v[96:99], v[36:39]
	v_mfma_f32_16x16x32_bf16 v[40:43], v[80:83], v[96:99], v[40:43]
	global_load_dwordx4 v[96:99], v[6:7], off offset:512
	s_waitcnt vmcnt(1)
	v_mfma_f32_16x16x32_bf16 v[48:51], v[92:95], v[88:91], v[48:51]
	v_mfma_f32_16x16x32_bf16 v[52:55], v[80:83], v[88:91], v[52:55]
	global_load_dwordx4 v[88:91], v[8:9], off offset:512
	s_waitcnt vmcnt(1)
	v_mfma_f32_16x16x32_bf16 v[56:59], v[92:95], v[96:99], v[56:59]
	v_mfma_f32_16x16x32_bf16 v[44:47], v[80:83], v[96:99], v[44:47]
	global_load_dwordx4 v[96:99], v[10:11], off offset:512
	s_waitcnt vmcnt(1)
	v_mfma_f32_16x16x32_bf16 v[60:63], v[92:95], v[88:91], v[60:63]
	v_mfma_f32_16x16x32_bf16 v[64:67], v[80:83], v[88:91], v[64:67]
	global_load_dwordx4 v[88:91], v[12:13], off offset:512
	s_waitcnt vmcnt(1)
; #define LAS __attribute__((address_space(3)))
; __global__ void __launch_bounds__(512, 2) fwd_kernel(Args a) {
;     ...
;         for (int ks = 0; ks < 11; ++ks) {
;             const bf16x8 wf0 = *(const bf16x8*)(wp + 32 * ks), wf1 = *(const bf16x8*)(wp + (size_t)16 * FF + 32 * ks);
; #pragma unroll
;             for (int rbk = 0; rbk < 8; ++rbk) { const bf16x8 af = *(const bf16x8*)(ap + (size_t)rbk * 16 * FF + 32 * ks);
;                 pa[0][rbk] = __builtin_amdgcn_mfma_f32_16x16x32_bf16(wf0, af, pa[0][rbk], 0, 0, 0); pa[1][rbk] = __builtin_amdgcn_mfma_f32_16x16x32_bf16(wf1, af, pa[1][rbk], 0, 0, 0); }
;             asm volatile("" ::: "memory");
;         }
;         LAS f32x4* red = (LAS f32x4*)lds;
; #pragma unroll
;         for (int j = 0; j < 2; ++j)
; #pragma unroll
;             for (int rbk = 0; rbk < 8; ++rbk) red[(wave * 16 + j * 8 + rbk) * 64 + lane] = pa[j][rbk];
;         __syncthreads();
	v_mfma_f32_16x16x32_bf16 v[68:71], v[92:95], v[96:99], v[68:71]
	v_mfma_f32_16x16x32_bf16 v[76:79], v[80:83], v[96:99], v[76:79]
	global_load_dwordx4 v[96:99], v[14:15], off offset:512
	s_waitcnt vmcnt(1)
	v_mfma_f32_16x16x32_bf16 v[84:87], v[92:95], v[88:91], v[84:87]
	v_mfma_f32_16x16x32_bf16 v[72:75], v[80:83], v[88:91], v[72:75]
	global_load_dwordx4 v[88:91], v[16:17], off offset:576
	s_waitcnt vmcnt(1)
	v_mfma_f32_16x16x32_bf16 v[24:27], v[80:83], v[96:99], v[24:27]
	global_load_dwordx4 v[80:83], v[0:1], off offset:576
	v_mfma_f32_16x16x32_bf16 v[20:23], v[92:95], v[96:99], v[20:23]
	global_load_dwordx4 v[92:95], v[18:19], off offset:576
	global_load_dwordx4 v[96:99], v[2:3], off offset:576
	s_waitcnt vmcnt(1)
	v_mfma_f32_16x16x32_bf16 v[28:31], v[88:91], v[92:95], v[28:31]
	v_mfma_f32_16x16x32_bf16 v[32:35], v[80:83], v[92:95], v[32:35]
	global_load_dwordx4 v[92:95], v[4:5], off offset:576
	s_waitcnt vmcnt(1)
	v_mfma_f32_16x16x32_bf16 v[36:39], v[88:91], v[96:99], v[36:39]
	v_mfma_f32_16x16x32_bf16 v[40:43], v[80:83], v[96:99], v[40:43]
	global_load_dwordx4 v[96:99], v[6:7], off offset:576
	s_waitcnt vmcnt(1)
	v_mfma_f32_16x16x32_bf16 v[48:51], v[88:91], v[92:95], v[48:51]
	v_mfma_f32_16x16x32_bf16 v[52:55], v[80:83], v[92:95], v[52:55]
	global_load_dwordx4 v[92:95], v[8:9], off offset:576
	s_waitcnt vmcnt(1)
	v_mfma_f32_16x16x32_bf16 v[56:59], v[88:91], v[96:99], v[56:59]
	v_mfma_f32_16x16x32_bf16 v[44:47], v[80:83], v[96:99], v[44:47]
	global_load_dwordx4 v[96:99], v[10:11], off offset:576
	s_waitcnt vmcnt(1)
	v_mfma_f32_16x16x32_bf16 v[60:63], v[88:91], v[92:95], v[60:63]
	v_mfma_f32_16x16x32_bf16 v[64:67], v[80:83], v[92:95], v[64:67]
	global_load_dwordx4 v[92:95], v[12:13], off offset:576
	s_waitcnt vmcnt(1)
	v_mfma_f32_16x16x32_bf16 v[68:71], v[88:91], v[96:99], v[68:71]
	v_mfma_f32_16x16x32_bf16 v[76:79], v[80:83], v[96:99], v[76:79]
	global_load_dwordx4 v[96:99], v[14:15], off offset:576
	s_waitcnt vmcnt(1)
	v_mfma_f32_16x16x32_bf16 v[84:87], v[88:91], v[92:95], v[84:87]
	v_mfma_f32_16x16x32_bf16 v[72:75], v[80:83], v[92:95], v[72:75]
	global_load_dwordx4 v[92:95], v[16:17], off offset:640
	s_waitcnt vmcnt(1)
	v_mfma_f32_16x16x32_bf16 v[24:27], v[80:83], v[96:99], v[24:27]
	global_load_dwordx4 v[80:83], v[0:1], off offset:640
	s_nop 0
	global_load_dwordx4 v[16:19], v[18:19], off offset:640
	v_mfma_f32_16x16x32_bf16 v[20:23], v[88:91], v[96:99], v[20:23]
	global_load_dwordx4 v[0:3], v[2:3], off offset:640
	s_waitcnt vmcnt(1)
	v_mfma_f32_16x16x32_bf16 v[28:31], v[92:95], v[16:19], v[28:31]
	v_mfma_f32_16x16x32_bf16 v[16:19], v[80:83], v[16:19], v[32:35]
	s_waitcnt vmcnt(0)
	v_mfma_f32_16x16x32_bf16 v[32:35], v[92:95], v[0:3], v[36:39]
	s_nop 2
	global_load_dwordx4 v[36:39], v[4:5], off offset:640
	v_mfma_f32_16x16x32_bf16 v[0:3], v[80:83], v[0:3], v[40:43]
	global_load_dwordx4 v[4:7], v[6:7], off offset:640
	s_waitcnt vmcnt(1)
	v_mfma_f32_16x16x32_bf16 v[40:43], v[92:95], v[36:39], v[48:51]
	s_nop 2
	global_load_dwordx4 v[48:51], v[8:9], off offset:640
	s_nop 0
	global_load_dwordx4 v[8:11], v[10:11], off offset:640
	v_mfma_f32_16x16x32_bf16 v[36:39], v[80:83], v[36:39], v[52:55]
	s_waitcnt vmcnt(2)
	v_mfma_f32_16x16x32_bf16 v[52:55], v[92:95], v[4:7], v[56:59]
	v_mfma_f32_16x16x32_bf16 v[4:7], v[80:83], v[4:7], v[44:47]
	s_nop 2
	global_load_dwordx4 v[44:47], v[12:13], off offset:640
	s_waitcnt vmcnt(2)
	v_mfma_f32_16x16x32_bf16 v[56:59], v[92:95], v[48:51], v[60:63]
	global_load_dwordx4 v[12:15], v[14:15], off offset:640
	v_mfma_f32_16x16x32_bf16 v[48:51], v[80:83], v[48:51], v[64:67]
	s_nop 2
	v_lshl_add_u32 v64, v154, 4, 0
	v_add_u32_e32 v65, s1, v64
	ds_write_b128 v65, v[28:31]
	ds_write_b128 v65, v[32:35] offset:1024
	ds_write_b128 v65, v[40:43] offset:2048
	s_waitcnt vmcnt(1)
	v_mfma_f32_16x16x32_bf16 v[28:31], v[92:95], v[44:47], v[84:87]
	s_lshr_b32 s1, s87, 8
	s_add_i32 s1, s1, s0
	s_lshl_b32 s0, s1, 4
	s_waitcnt vmcnt(0)
	v_mfma_f32_16x16x32_bf16 v[20:23], v[92:95], v[12:15], v[20:23]
	s_ashr_i32 s1, s0, 31
	s_lshl_b64 s[0:1], s[0:1], 2
	v_mfma_f32_16x16x32_bf16 v[60:63], v[92:95], v[8:11], v[68:71]
	ds_write_b128 v65, v[52:55] offset:3072
	ds_write_b128 v65, v[56:59] offset:4096
	s_nop 5
	ds_write_b128 v65, v[60:63] offset:5120
	ds_write_b128 v65, v[28:31] offset:6144
	ds_write_b128 v65, v[20:23] offset:7168
	ds_write_b128 v65, v[16:19] offset:8192
	v_mfma_f32_16x16x32_bf16 v[8:11], v[80:83], v[8:11], v[76:79]
	ds_write_b128 v65, v[0:3] offset:9216
	ds_write_b128 v65, v[36:39] offset:10240
	ds_write_b128 v65, v[4:7] offset:11264
	v_mov_b32_e32 v5, v159
	v_lshl_add_u32 v28, s18, 11, v64
	v_mfma_f32_16x16x32_bf16 v[0:3], v[80:83], v[44:47], v[72:75]
	ds_write_b128 v65, v[48:51] offset:12288
	s_nop 0
	ds_write_b128 v65, v[8:11] offset:13312
	s_nop 4
	ds_write_b128 v65, v[0:3] offset:14336
	v_mfma_f32_16x16x32_bf16 v[0:3], v[80:83], v[12:15], v[24:27]
	s_nop 7
	ds_write_b128 v65, v[0:3] offset:15360
	v_or_b32_e32 v0, s4, v157
	v_lshlrev_b32_e32 v0, 12, v0
	v_mov_b32_e32 v1, v159
	v_lshl_add_u64 v[0:1], s[8:9], 0, v[0:1]
	v_lshl_add_u64 v[0:1], v[0:1], 0, s[0:1]
	v_lshl_add_u64 v[0:1], v[0:1], 0, v[158:159]
	s_brev_b32 s4, 32
	v_add_co_u32_e32 v20, vcc, s4, v0
	s_waitcnt lgkmcnt(0)
	s_nop 0
	v_addc_co_u32_e32 v21, vcc, 0, v1, vcc
	s_barrier
; __global__ void __launch_bounds__(512, 2) fwd_kernel(Args a) {
;     ...
; #pragma unroll
;         for (int t = 0; t < 2; ++t) {
;             const int b = 2 * wave + t, j = b >> 3, rbk = b & 7;
;             f32x4 sm = (f32x4){0.f, 0.f, 0.f, 0.f};
; #pragma unroll
;             for (int w2 = 0; w2 < 8; ++w2) sm += red[(w2 * 16 + b) * 64 + lane];
;             float* p = out + (size_t)(MP + 16 * rbk + r16) * D + 16 * (cb0 + j) + 4 * q4;
;             *(f32x4*)p = *(const f32x4*)p + sm;
;         }
;         __syncthreads();
	global_load_dwordx4 v[0:3], v[20:21], off
	s_lshl_b32 s4, s18, 1
	s_or_b32 s4, s4, 1
	s_lshl_b32 s5, s4, 4
	s_and_b32 s5, s5, 0x70
	v_or_b32_e32 v4, s5, v157
	v_lshlrev_b32_e32 v4, 12, v4
	v_lshl_add_u64 v[4:5], s[8:9], 0, v[4:5]
	v_lshl_add_u64 v[4:5], v[4:5], 0, s[0:1]
	v_lshl_add_u64 v[4:5], v[4:5], 0, v[158:159]
	v_add_co_u32_e32 v22, vcc, 0x4000000, v4
	s_nop 1
	v_addc_co_u32_e32 v23, vcc, 0, v5, vcc
	global_load_dwordx4 v[4:7], v[22:23], off
	ds_read_b128 v[8:11], v28
	ds_read_b128 v[12:15], v28 offset:16384
	ds_read_b128 v[16:19], v28 offset:32768
	s_waitcnt lgkmcnt(2)
	v_pk_add_f32 v[8:9], v[8:9], 0 op_sel_hi:[1,0]
	v_pk_add_f32 v[10:11], v[10:11], 0 op_sel_hi:[1,0]
	s_waitcnt lgkmcnt(1)
	v_pk_add_f32 v[12:13], v[8:9], v[12:13]
	v_pk_add_f32 v[14:15], v[10:11], v[14:15]
	ds_read_b128 v[8:11], v28 offset:49152
	s_waitcnt lgkmcnt(1)
	v_pk_add_f32 v[16:17], v[12:13], v[16:17]
	v_add_u32_e32 v12, 0x10000, v28
	v_pk_add_f32 v[18:19], v[14:15], v[18:19]
	ds_read_b128 v[12:15], v12
	s_waitcnt lgkmcnt(1)
	v_pk_add_f32 v[16:17], v[16:17], v[8:9]
	v_add_u32_e32 v8, 0x14000, v28
	v_pk_add_f32 v[18:19], v[18:19], v[10:11]
	ds_read_b128 v[8:11], v8
	s_waitcnt lgkmcnt(1)
	v_pk_add_f32 v[26:27], v[16:17], v[12:13]
	v_add_u32_e32 v12, 0x18000, v28
	v_pk_add_f32 v[24:25], v[18:19], v[14:15]
	ds_read_b128 v[12:15], v12
	v_add_u32_e32 v16, 0x1c000, v28
	ds_read_b128 v[16:19], v16
	s_waitcnt lgkmcnt(2)
	v_pk_add_f32 v[10:11], v[24:25], v[10:11]
	v_pk_add_f32 v[8:9], v[26:27], v[8:9]
	s_waitcnt lgkmcnt(1)
	v_pk_add_f32 v[10:11], v[10:11], v[14:15]
	v_pk_add_f32 v[8:9], v[8:9], v[12:13]
	v_lshl_add_u32 v24, s4, 10, v64
	s_waitcnt lgkmcnt(0)
	v_pk_add_f32 v[12:13], v[10:11], v[18:19]
	v_pk_add_f32 v[14:15], v[8:9], v[16:17]
	ds_read_b128 v[8:11], v24
	s_waitcnt vmcnt(1)
	v_pk_add_f32 v[2:3], v[12:13], v[2:3]
	v_pk_add_f32 v[0:1], v[14:15], v[0:1]
	ds_read_b128 v[12:15], v24 offset:16384
	global_store_dwordx4 v[20:21], v[0:3], off
	ds_read_b128 v[0:3], v24 offset:32768
	s_waitcnt lgkmcnt(2)
	v_pk_add_f32 v[8:9], v[8:9], 0 op_sel_hi:[1,0]
	v_pk_add_f32 v[10:11], v[10:11], 0 op_sel_hi:[1,0]
	s_waitcnt lgkmcnt(1)
	v_pk_add_f32 v[12:13], v[8:9], v[12:13]
	v_pk_add_f32 v[14:15], v[10:11], v[14:15]
	ds_read_b128 v[8:11], v24 offset:49152
	s_waitcnt lgkmcnt(1)
	v_pk_add_f32 v[12:13], v[12:13], v[0:1]
	v_add_u32_e32 v0, 0x10000, v24
	v_pk_add_f32 v[14:15], v[14:15], v[2:3]
	ds_read_b128 v[0:3], v0
	s_waitcnt lgkmcnt(1)
	v_pk_add_f32 v[12:13], v[12:13], v[8:9]
	v_add_u32_e32 v8, 0x14000, v24
	v_pk_add_f32 v[14:15], v[14:15], v[10:11]
	ds_read_b128 v[8:11], v8
	s_waitcnt lgkmcnt(1)
	v_pk_add_f32 v[18:19], v[12:13], v[0:1]
	v_add_u32_e32 v0, 0x18000, v24
	v_pk_add_f32 v[16:17], v[14:15], v[2:3]
	ds_read_b128 v[0:3], v0
	v_add_u32_e32 v12, 0x1c000, v24
	ds_read_b128 v[12:15], v12
	s_waitcnt lgkmcnt(2)
	v_pk_add_f32 v[10:11], v[16:17], v[10:11]
	v_pk_add_f32 v[8:9], v[18:19], v[8:9]
	s_waitcnt lgkmcnt(1)
	v_pk_add_f32 v[2:3], v[10:11], v[2:3]
	v_pk_add_f32 v[0:1], v[8:9], v[0:1]
	s_waitcnt lgkmcnt(0)
	v_pk_add_f32 v[2:3], v[2:3], v[14:15]
	v_pk_add_f32 v[0:1], v[0:1], v[12:13]
	s_waitcnt vmcnt(1)
	v_pk_add_f32 v[2:3], v[2:3], v[6:7]
	v_pk_add_f32 v[0:1], v[0:1], v[4:5]
	global_store_dwordx4 v[22:23], v[0:3], off
	s_barrier
